# v52 + 20 B of unreachable padding so that all later code keeps its 64-byte placement
# speedup vs baseline: 1.0044x; 1.0044x over previous
.LBB0_78:
	s_mov_b64 s[2:3], 0x120000
	v_cmp_gt_u64_e32 vcc, s[2:3], v[172:173]
	s_and_saveexec_b64 s[2:3], vcc
	s_mov_b32 s34, 0xc200000
	s_cbranch_execz .LBB0_83
	v_readlane_b32 s6, v254, 51
	s_add_u32 s6, s64, s6
	v_readlane_b32 s7, v254, 52
	s_addc_u32 s7, s65, s7
	v_mov_b64_e32 v[4:5], v[172:173]
	v_lshl_add_u64 v[2:3], v[170:171], 1, s[6:7]
	s_mov_b64 s[6:7], 0
	s_cmp_eq_u32 s56, 0x100
	s_cbranch_scc0 .LBB0_81
	v_readfirstlane_b32 s100, v217
	v_readfirstlane_b32 s101, v230
	v_readlane_b32 s8, v254, 53
	v_readlane_b32 s9, v254, 54
	s_nop 3
	s_load_dwordx2 s[10:11], s[0:1], s100
	s_load_dwordx2 s[98:99], s[0:1], s101
	s_mov_b32 s6, 0xaaaaaaab
	s_mov_b32 s7, 0x38e38e39
	v_and_b32_e32 v4, 63, v208
	s_waitcnt lgkmcnt(0)
	v_readfirstlane_b32 s101, v172
	s_mul_hi_u32 s100, s101, s7
	s_lshr_b32 s100, s100, 11
	s_bitcmp1_b32 s100, 4
	s_cselect_b32 s42, s10, s98
	s_cselect_b32 s43, s11, s99
	v_add_u32_e32 v5, s101, v4
	s_mul_i32 s101, s100, 0x60
	v_mul_hi_u32 v6, v5, s6
	v_lshrrev_b32_e32 v6, 6, v6
	v_mul_u32_u24_e32 v7, 0x60, v6
	v_sub_u32_e32 v7, v5, v7
	v_subrev_u32_e32 v8, s101, v6
	s_lshr_b32 s101, s100, 5
	s_and_b32 s100, s100, 15
	s_lshl_b32 s101, s101, 4
	s_or_b32 s100, s100, s101
	s_mul_i32 s100, s100, 0x58
	v_add_u32_e32 v9, s100, v7
	v_mul_u32_u24_e32 v9, 0x58, v9
	v_add_lshl_u32 v9, v9, v8, 2
	v_cmp_gt_u32_e32 vcc, 0x58, v7
	s_mov_b64 s[100:101], vcc
	v_cmp_gt_u32_e32 vcc, 0x58, v8
	s_and_b64 vcc, vcc, s[100:101]
	s_nop 1
	v_cndmask_b32_e32 v9, 0, v9, vcc
	v_cndmask_b32_e64 v20, 0, -1, vcc
	global_load_dword v30, v9, s[42:43]
	v_readfirstlane_b32 s101, v172
	s_add_u32 s101, s101, 0x20000
	s_mul_hi_u32 s100, s101, s7
	s_lshr_b32 s100, s100, 11
	s_bitcmp1_b32 s100, 4
	s_cselect_b32 s42, s10, s98
	s_cselect_b32 s43, s11, s99
	v_add_u32_e32 v5, s101, v4
	s_mul_i32 s101, s100, 0x60
	v_mul_hi_u32 v6, v5, s6
	v_lshrrev_b32_e32 v6, 6, v6
	v_mul_u32_u24_e32 v7, 0x60, v6
	v_sub_u32_e32 v7, v5, v7
	v_subrev_u32_e32 v8, s101, v6
	s_lshr_b32 s101, s100, 5
	s_and_b32 s100, s100, 15
	s_lshl_b32 s101, s101, 4
	s_or_b32 s100, s100, s101
	s_mul_i32 s100, s100, 0x58
	v_add_u32_e32 v9, s100, v7
	v_mul_u32_u24_e32 v9, 0x58, v9
	v_add_lshl_u32 v9, v9, v8, 2
	v_cmp_gt_u32_e32 vcc, 0x58, v7
	s_mov_b64 s[100:101], vcc
	v_cmp_gt_u32_e32 vcc, 0x58, v8
	s_and_b64 vcc, vcc, s[100:101]
	s_nop 1
	v_cndmask_b32_e32 v9, 0, v9, vcc
	v_cndmask_b32_e64 v21, 0, -1, vcc
	global_load_dword v31, v9, s[42:43]
	v_readfirstlane_b32 s101, v172
	s_add_u32 s101, s101, 0x40000
	s_mul_hi_u32 s100, s101, s7
	s_lshr_b32 s100, s100, 11
	s_bitcmp1_b32 s100, 4
	s_cselect_b32 s42, s10, s98
	s_cselect_b32 s43, s11, s99
	v_add_u32_e32 v5, s101, v4
	s_mul_i32 s101, s100, 0x60
	v_mul_hi_u32 v6, v5, s6
	v_lshrrev_b32_e32 v6, 6, v6
	v_mul_u32_u24_e32 v7, 0x60, v6
	v_sub_u32_e32 v7, v5, v7
	v_subrev_u32_e32 v8, s101, v6
	s_lshr_b32 s101, s100, 5
	s_and_b32 s100, s100, 15
	s_lshl_b32 s101, s101, 4
	s_or_b32 s100, s100, s101
	s_mul_i32 s100, s100, 0x58
	v_add_u32_e32 v9, s100, v7
	v_mul_u32_u24_e32 v9, 0x58, v9
	v_add_lshl_u32 v9, v9, v8, 2
	v_cmp_gt_u32_e32 vcc, 0x58, v7
	s_mov_b64 s[100:101], vcc
	v_cmp_gt_u32_e32 vcc, 0x58, v8
	s_and_b64 vcc, vcc, s[100:101]
	s_nop 1
	v_cndmask_b32_e32 v9, 0, v9, vcc
	v_cndmask_b32_e64 v22, 0, -1, vcc
	global_load_dword v32, v9, s[42:43]
	v_readfirstlane_b32 s101, v172
	s_add_u32 s101, s101, 0x60000
	s_mul_hi_u32 s100, s101, s7
	s_lshr_b32 s100, s100, 11
	s_bitcmp1_b32 s100, 4
	s_cselect_b32 s42, s10, s98
	s_cselect_b32 s43, s11, s99
	v_add_u32_e32 v5, s101, v4
	s_mul_i32 s101, s100, 0x60
	v_mul_hi_u32 v6, v5, s6
	v_lshrrev_b32_e32 v6, 6, v6
	v_mul_u32_u24_e32 v7, 0x60, v6
	v_sub_u32_e32 v7, v5, v7
	v_subrev_u32_e32 v8, s101, v6
	s_lshr_b32 s101, s100, 5
	s_and_b32 s100, s100, 15
	s_lshl_b32 s101, s101, 4
	s_or_b32 s100, s100, s101
	s_mul_i32 s100, s100, 0x58
	v_add_u32_e32 v9, s100, v7
	v_mul_u32_u24_e32 v9, 0x58, v9
	v_add_lshl_u32 v9, v9, v8, 2
	v_cmp_gt_u32_e32 vcc, 0x58, v7
	s_mov_b64 s[100:101], vcc
	v_cmp_gt_u32_e32 vcc, 0x58, v8
	s_and_b64 vcc, vcc, s[100:101]
	s_nop 1
	v_cndmask_b32_e32 v9, 0, v9, vcc
	v_cndmask_b32_e64 v23, 0, -1, vcc
	global_load_dword v33, v9, s[42:43]
	v_readfirstlane_b32 s101, v172
	s_add_u32 s101, s101, 0x80000
	s_mul_hi_u32 s100, s101, s7
	s_lshr_b32 s100, s100, 11
	s_bitcmp1_b32 s100, 4
	s_cselect_b32 s42, s10, s98
	s_cselect_b32 s43, s11, s99
	v_add_u32_e32 v5, s101, v4
	s_mul_i32 s101, s100, 0x60
	v_mul_hi_u32 v6, v5, s6
	v_lshrrev_b32_e32 v6, 6, v6
	v_mul_u32_u24_e32 v7, 0x60, v6
	v_sub_u32_e32 v7, v5, v7
	v_subrev_u32_e32 v8, s101, v6
	s_lshr_b32 s101, s100, 5
	s_and_b32 s100, s100, 15
	s_lshl_b32 s101, s101, 4
	s_or_b32 s100, s100, s101
	s_mul_i32 s100, s100, 0x58
	v_add_u32_e32 v9, s100, v7
	v_mul_u32_u24_e32 v9, 0x58, v9
	v_add_lshl_u32 v9, v9, v8, 2
	v_cmp_gt_u32_e32 vcc, 0x58, v7
	s_mov_b64 s[100:101], vcc
	v_cmp_gt_u32_e32 vcc, 0x58, v8
	s_and_b64 vcc, vcc, s[100:101]
	s_nop 1
	v_cndmask_b32_e32 v9, 0, v9, vcc
	v_cndmask_b32_e64 v24, 0, -1, vcc
	global_load_dword v34, v9, s[42:43]
	v_readfirstlane_b32 s101, v172
	s_add_u32 s101, s101, 0xa0000
	s_mul_hi_u32 s100, s101, s7
	s_lshr_b32 s100, s100, 11
	s_bitcmp1_b32 s100, 4
	s_cselect_b32 s42, s10, s98
	s_cselect_b32 s43, s11, s99
	v_add_u32_e32 v5, s101, v4
	s_mul_i32 s101, s100, 0x60
	v_mul_hi_u32 v6, v5, s6
	v_lshrrev_b32_e32 v6, 6, v6
	v_mul_u32_u24_e32 v7, 0x60, v6
	v_sub_u32_e32 v7, v5, v7
	v_subrev_u32_e32 v8, s101, v6
	s_lshr_b32 s101, s100, 5
	s_and_b32 s100, s100, 15
	s_lshl_b32 s101, s101, 4
	s_or_b32 s100, s100, s101
	s_mul_i32 s100, s100, 0x58
	v_add_u32_e32 v9, s100, v7
	v_mul_u32_u24_e32 v9, 0x58, v9
	v_add_lshl_u32 v9, v9, v8, 2
	v_cmp_gt_u32_e32 vcc, 0x58, v7
	s_mov_b64 s[100:101], vcc
	v_cmp_gt_u32_e32 vcc, 0x58, v8
	s_and_b64 vcc, vcc, s[100:101]
	s_nop 1
	v_cndmask_b32_e32 v9, 0, v9, vcc
	v_cndmask_b32_e64 v25, 0, -1, vcc
	global_load_dword v35, v9, s[42:43]
	v_readfirstlane_b32 s101, v172
	s_add_u32 s101, s101, 0xc0000
	s_mul_hi_u32 s100, s101, s7
	s_lshr_b32 s100, s100, 11
	s_bitcmp1_b32 s100, 4
	s_cselect_b32 s42, s10, s98
	s_cselect_b32 s43, s11, s99
	v_add_u32_e32 v5, s101, v4
	s_mul_i32 s101, s100, 0x60
	v_mul_hi_u32 v6, v5, s6
	v_lshrrev_b32_e32 v6, 6, v6
	v_mul_u32_u24_e32 v7, 0x60, v6
	v_sub_u32_e32 v7, v5, v7
	v_subrev_u32_e32 v8, s101, v6
	s_lshr_b32 s101, s100, 5
	s_and_b32 s100, s100, 15
	s_lshl_b32 s101, s101, 4
	s_or_b32 s100, s100, s101
	s_mul_i32 s100, s100, 0x58
	v_add_u32_e32 v9, s100, v7
	v_mul_u32_u24_e32 v9, 0x58, v9
	v_add_lshl_u32 v9, v9, v8, 2
	v_cmp_gt_u32_e32 vcc, 0x58, v7
	s_mov_b64 s[100:101], vcc
	v_cmp_gt_u32_e32 vcc, 0x58, v8
	s_and_b64 vcc, vcc, s[100:101]
	s_nop 1
	v_cndmask_b32_e32 v9, 0, v9, vcc
	v_cndmask_b32_e64 v26, 0, -1, vcc
	global_load_dword v36, v9, s[42:43]
	v_readfirstlane_b32 s101, v172
	s_add_u32 s101, s101, 0xe0000
	s_mul_hi_u32 s100, s101, s7
	s_lshr_b32 s100, s100, 11
	s_bitcmp1_b32 s100, 4
	s_cselect_b32 s42, s10, s98
	s_cselect_b32 s43, s11, s99
	v_add_u32_e32 v5, s101, v4
	s_mul_i32 s101, s100, 0x60
	v_mul_hi_u32 v6, v5, s6
	v_lshrrev_b32_e32 v6, 6, v6
	v_mul_u32_u24_e32 v7, 0x60, v6
	v_sub_u32_e32 v7, v5, v7
	v_subrev_u32_e32 v8, s101, v6
	s_lshr_b32 s101, s100, 5
	s_and_b32 s100, s100, 15
	s_lshl_b32 s101, s101, 4
	s_or_b32 s100, s100, s101
	s_mul_i32 s100, s100, 0x58
	v_add_u32_e32 v9, s100, v7
	v_mul_u32_u24_e32 v9, 0x58, v9
	v_add_lshl_u32 v9, v9, v8, 2
	v_cmp_gt_u32_e32 vcc, 0x58, v7
	s_mov_b64 s[100:101], vcc
	v_cmp_gt_u32_e32 vcc, 0x58, v8
	s_and_b64 vcc, vcc, s[100:101]
	s_nop 1
	v_cndmask_b32_e32 v9, 0, v9, vcc
	v_cndmask_b32_e64 v27, 0, -1, vcc
	global_load_dword v37, v9, s[42:43]
	v_readfirstlane_b32 s101, v172
	s_add_u32 s101, s101, 0x100000
	s_mul_hi_u32 s100, s101, s7
	s_lshr_b32 s100, s100, 11
	s_bitcmp1_b32 s100, 4
	s_cselect_b32 s42, s10, s98
	s_cselect_b32 s43, s11, s99
	v_add_u32_e32 v5, s101, v4
	s_mul_i32 s101, s100, 0x60
	v_mul_hi_u32 v6, v5, s6
	v_lshrrev_b32_e32 v6, 6, v6
	v_mul_u32_u24_e32 v7, 0x60, v6
	v_sub_u32_e32 v7, v5, v7
	v_subrev_u32_e32 v8, s101, v6
	s_lshr_b32 s101, s100, 5
	s_and_b32 s100, s100, 15
	s_lshl_b32 s101, s101, 4
	s_or_b32 s100, s100, s101
	s_mul_i32 s100, s100, 0x58
	v_add_u32_e32 v9, s100, v7
	v_mul_u32_u24_e32 v9, 0x58, v9
	v_add_lshl_u32 v9, v9, v8, 2
	v_cmp_gt_u32_e32 vcc, 0x58, v7
	s_mov_b64 s[100:101], vcc
	v_cmp_gt_u32_e32 vcc, 0x58, v8
	s_and_b64 vcc, vcc, s[100:101]
	s_nop 1
	v_cndmask_b32_e32 v9, 0, v9, vcc
	v_cndmask_b32_e64 v28, 0, -1, vcc
	global_load_dword v38, v9, s[42:43]
	s_waitcnt vmcnt(8)
	v_and_b32_e32 v30, v30, v20
	v_bfe_u32 v5, v30, 16, 1
	v_add3_u32 v5, v30, v5, s90
	global_store_short_d16_hi v[2:3], v5, off
	v_lshl_add_u64 v[2:3], v[2:3], 0, s[8:9]
	s_waitcnt vmcnt(8)
	v_and_b32_e32 v31, v31, v21
	v_bfe_u32 v5, v31, 16, 1
	v_add3_u32 v5, v31, v5, s90
	global_store_short_d16_hi v[2:3], v5, off
	v_lshl_add_u64 v[2:3], v[2:3], 0, s[8:9]
	s_waitcnt vmcnt(8)
	v_and_b32_e32 v32, v32, v22
	v_bfe_u32 v5, v32, 16, 1
	v_add3_u32 v5, v32, v5, s90
	global_store_short_d16_hi v[2:3], v5, off
	v_lshl_add_u64 v[2:3], v[2:3], 0, s[8:9]
	s_waitcnt vmcnt(8)
	v_and_b32_e32 v33, v33, v23
	v_bfe_u32 v5, v33, 16, 1
	v_add3_u32 v5, v33, v5, s90
	global_store_short_d16_hi v[2:3], v5, off
	v_lshl_add_u64 v[2:3], v[2:3], 0, s[8:9]
	s_waitcnt vmcnt(8)
	v_and_b32_e32 v34, v34, v24
	v_bfe_u32 v5, v34, 16, 1
	v_add3_u32 v5, v34, v5, s90
	global_store_short_d16_hi v[2:3], v5, off
	v_lshl_add_u64 v[2:3], v[2:3], 0, s[8:9]
	s_waitcnt vmcnt(8)
	v_and_b32_e32 v35, v35, v25
	v_bfe_u32 v5, v35, 16, 1
	v_add3_u32 v5, v35, v5, s90
	global_store_short_d16_hi v[2:3], v5, off
	v_lshl_add_u64 v[2:3], v[2:3], 0, s[8:9]
	s_waitcnt vmcnt(8)
	v_and_b32_e32 v36, v36, v26
	v_bfe_u32 v5, v36, 16, 1
	v_add3_u32 v5, v36, v5, s90
	global_store_short_d16_hi v[2:3], v5, off
	v_lshl_add_u64 v[2:3], v[2:3], 0, s[8:9]
	s_waitcnt vmcnt(8)
	v_and_b32_e32 v37, v37, v27
	v_bfe_u32 v5, v37, 16, 1
	v_add3_u32 v5, v37, v5, s90
	global_store_short_d16_hi v[2:3], v5, off
	v_lshl_add_u64 v[2:3], v[2:3], 0, s[8:9]
	s_waitcnt vmcnt(8)
	v_and_b32_e32 v38, v38, v28
	v_bfe_u32 v5, v38, 16, 1
	v_add3_u32 v5, v38, v5, s90
	global_store_short_d16_hi v[2:3], v5, off
	s_branch .LBB0_83
	s_nop 0
	s_nop 0
	s_nop 0
	s_nop 0
	s_nop 0
